# NSA tile fast path: 32-term f32 row-sum as packed v_pk_add_f32 tree (16 instrs instead of 32), f32 throughout
# baseline (speedup 1.0000x reference)
; DI float fexp2(float x) { return __builtin_amdgcn_exp2f(x); }
; DI void softmax_lazy(f32x16 (&s)[2], float& m, float& l, f32x16 (&o)[2], int hh) {
;     ...
;     float sum = 0.f;
; #pragma unroll
;     for (int t = 0; t < 2; ++t)
; #pragma unroll
;         for (int i = 0; i < 16; ++i) { s[t][i] = fexp2(s[t][i]); sum += s[t][i]; }
;     sum += __shfl_xor(sum, 32);
;     l += sum;
.LBB0_2419:
	v_add3_u32 v0, s0, v212, v241
	ds_read_b128 v[56:59], v0 offset:44544
	ds_read_b128 v[60:63], v0 offset:49152
	v_exp_f32_e32 v160, v160
	v_exp_f32_e32 v161, v161
	v_exp_f32_e32 v162, v162
	v_exp_f32_e32 v163, v163
	v_exp_f32_e32 v164, v164
	v_exp_f32_e32 v165, v165
	v_exp_f32_e32 v166, v166
	v_exp_f32_e32 v167, v167
	v_pk_add_f32 v[20:21], v[160:161], v[162:163]
	v_pk_add_f32 v[22:23], v[164:165], v[166:167]
	v_pk_add_f32 v[2:3], v[20:21], v[22:23]
	v_cvt_pk_bf16_f32 v8, v160, v161
	v_cvt_pk_bf16_f32 v9, v162, v163
	v_cvt_pk_bf16_f32 v10, v164, v165
	v_cvt_pk_bf16_f32 v11, v166, v167
	v_exp_f32_e32 v168, v168
	v_exp_f32_e32 v169, v169
	v_exp_f32_e32 v170, v170
	v_exp_f32_e32 v171, v171
	s_waitcnt lgkmcnt(0)
	v_mfma_f32_32x32x16_bf16 v[128:143], v[56:59], v[8:11], v[128:143]
	v_exp_f32_e32 v172, v172
	v_exp_f32_e32 v173, v173
	v_exp_f32_e32 v174, v174
	v_exp_f32_e32 v175, v175
	v_mfma_f32_32x32x16_bf16 v[112:127], v[60:63], v[8:11], v[112:127]
	ds_read_b128 v[64:67], v0 offset:44576
	ds_read_b128 v[68:71], v0 offset:49184
	v_pk_add_f32 v[20:21], v[168:169], v[170:171]
	v_pk_add_f32 v[22:23], v[172:173], v[174:175]
	v_pk_add_f32 v[20:21], v[20:21], v[22:23]
	v_pk_add_f32 v[2:3], v[2:3], v[20:21]
	v_cvt_pk_bf16_f32 v12, v168, v169
	v_cvt_pk_bf16_f32 v13, v170, v171
	v_cvt_pk_bf16_f32 v14, v172, v173
	v_cvt_pk_bf16_f32 v15, v174, v175
	v_exp_f32_e32 v144, v144
	v_exp_f32_e32 v145, v145
	v_exp_f32_e32 v146, v146
	v_exp_f32_e32 v147, v147
	s_waitcnt lgkmcnt(0)
	v_mfma_f32_32x32x16_bf16 v[128:143], v[64:67], v[12:15], v[128:143]
	v_exp_f32_e32 v148, v148
	v_exp_f32_e32 v149, v149
	v_exp_f32_e32 v150, v150
	v_exp_f32_e32 v151, v151
	v_mfma_f32_32x32x16_bf16 v[112:127], v[68:71], v[12:15], v[112:127]
	ds_read_b128 v[72:75], v0 offset:44608
	ds_read_b128 v[76:79], v0 offset:49216
	v_pk_add_f32 v[20:21], v[144:145], v[146:147]
	v_pk_add_f32 v[22:23], v[148:149], v[150:151]
	v_pk_add_f32 v[20:21], v[20:21], v[22:23]
	v_pk_add_f32 v[2:3], v[2:3], v[20:21]
	v_cvt_pk_bf16_f32 v16, v144, v145
	v_cvt_pk_bf16_f32 v17, v146, v147
	v_cvt_pk_bf16_f32 v18, v148, v149
	v_cvt_pk_bf16_f32 v19, v150, v151
	v_exp_f32_e32 v152, v152
	v_exp_f32_e32 v153, v153
	v_exp_f32_e32 v154, v154
	v_exp_f32_e32 v155, v155
	s_waitcnt lgkmcnt(0)
	v_mfma_f32_32x32x16_bf16 v[128:143], v[72:75], v[16:19], v[128:143]
	v_exp_f32_e32 v156, v156
	v_exp_f32_e32 v157, v157
	v_exp_f32_e32 v158, v158
	v_exp_f32_e32 v159, v159
	v_mfma_f32_32x32x16_bf16 v[112:127], v[76:79], v[16:19], v[112:127]
	ds_read_b128 v[144:147], v0 offset:44640
	ds_read_b128 v[148:151], v0 offset:49248
	v_pk_add_f32 v[20:21], v[152:153], v[154:155]
	v_pk_add_f32 v[22:23], v[156:157], v[158:159]
	v_pk_add_f32 v[20:21], v[20:21], v[22:23]
	v_pk_add_f32 v[2:3], v[2:3], v[20:21]
	v_add_f32_e32 v3, v2, v3
	v_mov_b32_e32 v7, v3
	v_cvt_pk_bf16_f32 v52, v152, v153
	v_cvt_pk_bf16_f32 v53, v154, v155
	v_cvt_pk_bf16_f32 v54, v156, v157
	v_cvt_pk_bf16_f32 v55, v158, v159
	v_permlane32_swap_b32_e32 v7, v3
	v_add_f32_e32 v3, v3, v7
	v_add_f32_e32 v245, v245, v3
	s_waitcnt lgkmcnt(0)
	v_mfma_f32_32x32x16_bf16 v[128:143], v[144:147], v[52:55], v[128:143]
	v_mfma_f32_32x32x16_bf16 v[112:127], v[148:151], v[52:55], v[112:127]
